# phase 3: workgroups on odd XCDs run differential attention first and spatial gating last (even XCDs unchanged), overlapping the HBM-bound gating pass with the other half's attention
# baseline (speedup 1.0000x reference)
; #define LDSP(T, p) ((__attribute__((address_space(3))) T*)(p))
; DI void sg_phase(const Params& p, lds_t* shm) {
;   const int tid = tidx(), wid = tid >> 6, lane = tid & 63, h = lane >> 5, l31 = lane & 31;
;   const bf16_t* Vs = slot(p, 5); bf16_t* U = slot(p, 4); const bf16_t* wm = (const bf16_t*)(p.ws + OFF_WM);
;   __attribute__((address_space(3))) float* stats = LDSP(float, shm + 32768);
;   const unsigned q4 = (lane & 15) >> 2, pp = lane & 3, blk = (lane >> 4) & 1;
;   for (int w = blockIdx.x; w < T_TOK / 128; w += gridDim.x) {
;     __syncthreads();
;     for (int t4 = 0; t4 < 16; t4 += 4) {
;       u32x4 rv[4][2];
; #pragma unroll
;       for (int q = 0; q < 4; ++q) { const u32x4* rp = (const u32x4*)(Vs + (size_t)(w * 128 + wid * 16 + t4 + q) * DM); rv[q][0] = rp[lane]; rv[q][1] = rp[lane + 64]; }
;       float sm[4], sq[4];
; #pragma unroll
;       for (int q = 0; q < 4; ++q) { float a0 = 0.f, a1 = 0.f;
; #pragma unroll
;         for (int i = 0; i < 2; ++i)
; #pragma unroll
;           for (int e = 0; e < 4; ++e) { const float a = bf_lo(rv[q][i][e]), bb = bf_hi(rv[q][i][e]); a0 += a + bb; a1 += a * a + bb * bb; }
;         sm[q] = a0; sq[q] = a1; }
; #pragma unroll
;       for (int q = 0; q < 4; ++q) { sm[q] = wave_sum(sm[q]); sq[q] = wave_sum(sq[q]); }
; #pragma unroll
;       for (int q = 0; q < 4; ++q) { const int j = wid * 16 + t4 + q; const float mu = sm[q] * (1.0f / DM), var = fmaxf(sq[q] * (1.0f / DM) - mu * mu, 0.f);
;         if (lane == 0) { stats[2 * j] = mu; stats[2 * j + 1] = rsqrtf(var + 1e-5f); } }
;     }
;     u32x4 raw[4];
; #pragma unroll
;     for (int i = 0; i < 4; ++i) { const int idx = tid + 512 * i, row = idx >> 4, ch = idx & 15; raw[i] = *(const u32x4*)(Vs + (size_t)(w * 128 + row) * DM + ch * 8); }
;     for (int g = 0; g < 8; ++g) {
;       __syncthreads();
; #pragma unroll
;       for (int i = 0; i < 4; ++i) {
;         const int idx = tid + 512 * i, row = idx >> 4, ch = idx & 15; const int c0 = g * 128 + ch * 8;
;         const u32x4 v = raw[i];
;         const float mu = stats[2 * row], rs = stats[2 * row + 1];
;         const f32x4 g0 = *(const f32x4*)(p.ln_g + c0), g1 = *(const f32x4*)(p.ln_g + c0 + 4), b0 = *(const f32x4*)(p.ln_b + c0), b1 = *(const f32x4*)(p.ln_b + c0 + 4);
;         u32x4 o;
;         o.x = pk2((bf_lo(v.x) - mu) * rs * g0[0] + b0[0], (bf_hi(v.x) - mu) * rs * g0[1] + b0[1]);
.LBB0_385:
	s_or_b64 exec, exec, s[4:5]
	v_readlane_b32 s0, v254, 20
	v_readlane_b32 s1, v254, 21
	v_mov_b32_e32 v0, v212
	s_and_b64 vcc, exec, s[0:1]
	s_barrier
	s_mov_b32 s99, 0
	s_cbranch_vccnz .LBB0_402
	s_getreg_b32 s99, hwreg(20, 0, 4)
	s_and_b32 s99, s99, 1
	s_cmp_eq_u32 s99, 0
	s_cbranch_scc1 .Lp3_sg_entry
	v_writelane_b32 v194, s40, 0
	v_writelane_b32 v194, s41, 1
	v_writelane_b32 v194, s42, 2
	v_writelane_b32 v194, s43, 3
	v_writelane_b32 v194, s46, 4
	v_writelane_b32 v194, s47, 5
	s_branch .LBB0_402
.Lp3_sg_entry:
	v_mbcnt_hi_u32_b32 v3, -1, v154
	v_and_b32_e32 v5, 64, v3
	v_xor_b32_e32 v4, 32, v3
	v_add_u32_e32 v5, 64, v5
	v_cmp_lt_i32_e32 vcc, v4, v5
	s_add_u32 s0, s74, 0x18000000
	v_and_b32_e32 v2, 63, v0
	v_cndmask_b32_e32 v4, v3, v4, vcc
	v_lshlrev_b32_e32 v71, 2, v4
	v_xor_b32_e32 v4, 16, v3
	v_cmp_lt_i32_e32 vcc, v4, v5
	s_addc_u32 s1, s75, 0
	v_lshlrev_b32_e32 v48, 4, v2
	v_cndmask_b32_e32 v4, v3, v4, vcc
	v_lshlrev_b32_e32 v72, 2, v4
	v_xor_b32_e32 v4, 8, v3
	v_cmp_lt_i32_e32 vcc, v4, v5
	v_mov_b32_e32 v49, 0
	v_lshl_add_u64 v[50:51], s[0:1], 0, v[48:49]
	v_cndmask_b32_e32 v4, v3, v4, vcc
	v_lshlrev_b32_e32 v73, 2, v4
	v_xor_b32_e32 v4, 4, v3
	v_cmp_lt_i32_e32 vcc, v4, v5
	v_ashrrev_i32_e32 v8, 6, v0
	v_and_b32_e32 v1, 31, v0
	v_cndmask_b32_e32 v4, v3, v4, vcc
	v_lshlrev_b32_e32 v74, 2, v4
	v_xor_b32_e32 v4, 2, v3
	v_cmp_lt_i32_e32 vcc, v4, v5
	v_bfe_u32 v7, v0, 5, 1
	v_bfe_u32 v6, v0, 2, 2
	v_cndmask_b32_e32 v4, v3, v4, vcc
	v_lshlrev_b32_e32 v75, 2, v4
	v_xor_b32_e32 v4, 1, v3
	v_cmp_lt_i32_e32 vcc, v4, v5
	v_lshl_add_u32 v82, v6, 6, 0
	v_ashrrev_i32_e32 v84, 4, v0
	v_cndmask_b32_e32 v3, v3, v4, vcc
	v_cmp_eq_u32_e32 vcc, 0, v2
	v_lshlrev_b32_e32 v2, 4, v0
	v_and_b32_e32 v48, 0xf0, v2
	v_and_b32_e32 v2, 15, v0
	v_lshlrev_b32_e32 v77, 3, v2
	v_lshlrev_b32_e32 v2, 7, v0
	v_and_b32_e32 v2, 0x600, v2
	v_add_u32_e32 v9, 0, v2
	v_and_b32_e32 v2, 3, v8
	v_lshlrev_b32_e32 v76, 2, v3
	v_cmp_gt_u32_e64 s[4:5], 2, v2
	v_lshl_or_b32 v79, v2, 5, v1
	v_lshlrev_b32_e32 v2, 4, v7
	v_mov_b32_e32 v3, v49
	v_lshl_add_u64 v[52:53], s[0:1], 0, v[48:49]
	v_lshl_add_u64 v[2:3], s[74:75], 0, v[2:3]
	s_mov_b64 s[0:1], 0x300000
	v_lshl_add_u64 v[54:55], v[2:3], 0, s[0:1]
	v_lshrrev_b32_e32 v1, 3, v0
	v_bfe_u32 v2, v0, 1, 1
	v_and_or_b32 v81, v1, 2, v2
	v_and_b32_e32 v1, 32, v0
	v_lshlrev_b32_e32 v2, 4, v81
	v_xad_u32 v10, v2, v1, v82
	v_add_u32_e32 v1, 0x200, v0
	v_ashrrev_i32_e32 v85, 4, v1
	v_add_u32_e32 v1, 0x400, v0
	v_ashrrev_i32_e32 v86, 4, v1
	v_add_u32_e32 v1, 0x600, v0
	v_ashrrev_i32_e32 v87, 4, v1
	v_lshlrev_b32_e32 v1, 8, v84
	v_lshlrev_b32_e32 v3, 6, v84
	v_and_b32_e32 v1, 0xfffff800, v1
	v_and_b32_e32 v3, 0x1c0, v3
	v_add3_u32 v13, v9, v1, v3
	v_lshlrev_b32_e32 v1, 8, v85
	v_lshlrev_b32_e32 v3, 6, v85
	v_and_b32_e32 v1, 0xfffff800, v1
	v_and_b32_e32 v3, 0x1c0, v3
	v_add3_u32 v16, v9, v1, v3
	v_lshlrev_b32_e32 v1, 8, v86
	v_lshlrev_b32_e32 v3, 6, v86
	v_and_b32_e32 v1, 0xfffff800, v1
	v_and_b32_e32 v3, 0x1c0, v3
	v_ashrrev_i32_e32 v5, 8, v0
	v_lshrrev_b32_e32 v12, 2, v84
	v_lshrrev_b32_e32 v15, 2, v85
	v_lshrrev_b32_e32 v18, 2, v86
	v_add3_u32 v19, v9, v1, v3
	v_lshlrev_b32_e32 v1, 8, v87
	v_lshlrev_b32_e32 v3, 6, v87
	v_lshrrev_b32_e32 v21, 2, v87
	v_lshlrev_b32_e32 v4, 3, v0
	v_lshlrev_b32_e32 v48, 3, v7
	v_lshlrev_b32_e32 v2, 6, v5
	v_xor_b32_e32 v12, v12, v0
	v_xor_b32_e32 v15, v15, v0
	v_xor_b32_e32 v18, v18, v0
	v_and_b32_e32 v1, 0xfffff800, v1
	v_and_b32_e32 v3, 0x1c0, v3
	v_xor_b32_e32 v0, v21, v0
	v_lshlrev_b32_e32 v80, 10, v5
	v_and_b32_e32 v83, 8, v4
	v_lshl_add_u64 v[4:5], s[74:75], 0, v[48:49]
	v_lshlrev_b32_e32 v0, 4, v0
	v_add3_u32 v9, v9, v1, v3
	v_ashrrev_i32_e32 v3, 31, v2
	v_lshlrev_b32_e32 v12, 4, v12
	v_lshlrev_b32_e32 v15, 4, v15
	v_lshlrev_b32_e32 v18, 4, v18
	v_and_b32_e32 v21, 48, v0
	v_lshl_add_u64 v[0:1], v[2:3], 1, v[4:5]
	s_mov_b64 s[0:1], 0x14000000
	v_lshlrev_b32_e32 v70, 4, v8
	v_lshlrev_b32_e32 v8, 7, v8
	v_lshlrev_b32_e32 v11, 3, v84
	v_and_b32_e32 v12, 48, v12
	v_lshlrev_b32_e32 v14, 3, v85
	v_and_b32_e32 v15, 48, v15
	v_lshlrev_b32_e32 v17, 3, v86
	v_and_b32_e32 v18, 48, v18
	v_lshlrev_b32_e32 v20, 3, v87
	v_lshl_add_u64 v[56:57], v[0:1], 0, s[0:1]
	v_lshlrev_b32_e32 v0, 8, v6
	s_mov_b32 s9, 0
	v_cndmask_b32_e64 v78, 8, 4, s[4:5]
	v_add3_u32 v88, v10, v83, v80
	v_or_b32_e32 v89, v48, v6
	v_lshl_or_b32 v90, v7, 11, v0
	s_mov_b32 s10, 0x3a800000
	s_mov_b32 s2, 0x800000
	v_add_u32_e32 v91, 0, v11
	v_add_u32_e32 v92, v13, v12
	v_add_u32_e32 v93, 0, v14
	v_add_u32_e32 v94, v16, v15
	v_add_u32_e32 v95, 0, v17
	v_add_u32_e32 v96, v19, v18
	v_add_u32_e32 v97, 0, v20
	v_add_u32_e32 v98, v9, v21
	v_add_u32_e32 v99, 0, v8
	s_mov_b32 s3, s68

; DI float bf_lo(unsigned u) { return __uint_as_float(u << 16); }
; DI float bf_hi(unsigned u) { return __uint_as_float(u & 0xffff0000u); }
; DI void st_bf4(bf16_t* p, f32x4 v) { u32x2 w; w.x = pk2(v[0], v[1]); w.y = pk2(v[2], v[3]); *(u32x2*)p = w; }
; DI void sg_phase(const Params& p, lds_t* shm) {
;     ...
;       const int tok = w * 128 + ib * 32 + l31; const float bias = p.sg_b[g * 128 + ib * 32 + l31];
; #pragma unroll
;       for (int cc = 0; cc < 2; ++cc)
; #pragma unroll
;         for (int g4 = 0; g4 < 4; ++g4) {
;           bf16_t* up = U + (size_t)tok * DM + g * 128 + 32 * (2 * chalf + cc) + 8 * g4 + 4 * h;
;           const u32x2 uu = *(const u32x2*)up; f32x4 o;
;           o[0] = bf_lo(uu.x) * (acc[cc][4 * g4 + 0] + bias); o[1] = bf_hi(uu.x) * (acc[cc][4 * g4 + 1] + bias);
;           o[2] = bf_lo(uu.y) * (acc[cc][4 * g4 + 2] + bias); o[3] = bf_hi(uu.y) * (acc[cc][4 * g4 + 3] + bias);
;           st_bf4(up, o);
;         }
;     }
.Lsg_done:
	s_or_b64 exec, exec, s[6:7]
	s_lshl_b32 s8, s1, 1
	v_lshl_add_u64 v[68:69], v[66:67], 0, s[8:9]
	v_lshl_add_u64 v[68:69], v[68:69], 0, v[216:217]
	s_waitcnt vmcnt(8)
	s_nop 7
	s_nop 7
	v_pk_add_f32 v[16:17], v[16:17], v[194:195] op_sel_hi:[1,0]
	v_pk_add_f32 v[18:19], v[18:19], v[194:195] op_sel_hi:[1,0]
	v_pk_add_f32 v[20:21], v[20:21], v[194:195] op_sel_hi:[1,0]
	v_pk_add_f32 v[22:23], v[22:23], v[194:195] op_sel_hi:[1,0]
	v_pk_add_f32 v[24:25], v[24:25], v[194:195] op_sel_hi:[1,0]
	v_pk_add_f32 v[26:27], v[26:27], v[194:195] op_sel_hi:[1,0]
	v_pk_add_f32 v[28:29], v[28:29], v[194:195] op_sel_hi:[1,0]
	v_pk_add_f32 v[30:31], v[30:31], v[194:195] op_sel_hi:[1,0]
	v_pk_add_f32 v[0:1], v[0:1], v[194:195] op_sel_hi:[1,0]
	v_pk_add_f32 v[2:3], v[2:3], v[194:195] op_sel_hi:[1,0]
	v_pk_add_f32 v[4:5], v[4:5], v[194:195] op_sel_hi:[1,0]
	v_pk_add_f32 v[6:7], v[6:7], v[194:195] op_sel_hi:[1,0]
	v_pk_add_f32 v[8:9], v[8:9], v[194:195] op_sel_hi:[1,0]
	v_pk_add_f32 v[10:11], v[10:11], v[194:195] op_sel_hi:[1,0]
	v_pk_add_f32 v[12:13], v[12:13], v[194:195] op_sel_hi:[1,0]
	v_pk_add_f32 v[14:15], v[14:15], v[194:195] op_sel_hi:[1,0]
	s_nop 1
	v_permlane32_swap_b32_e32 v16, v20
	v_permlane32_swap_b32_e32 v17, v21
	v_permlane32_swap_b32_e32 v18, v22
	v_permlane32_swap_b32_e32 v19, v23
	v_permlane32_swap_b32_e32 v24, v28
	v_permlane32_swap_b32_e32 v25, v29
	v_permlane32_swap_b32_e32 v26, v30
	v_permlane32_swap_b32_e32 v27, v31
	v_permlane32_swap_b32_e32 v0, v4
	v_permlane32_swap_b32_e32 v1, v5
	v_permlane32_swap_b32_e32 v2, v6
	v_permlane32_swap_b32_e32 v3, v7
	v_permlane32_swap_b32_e32 v8, v12
	v_permlane32_swap_b32_e32 v9, v13
	v_permlane32_swap_b32_e32 v10, v14
	v_permlane32_swap_b32_e32 v11, v15
	s_waitcnt vmcnt(7)
	v_lshlrev_b32_e32 v100, 16, v196
	v_and_b32_e32 v101, 0xffff0000, v196
	v_lshlrev_b32_e32 v102, 16, v197
	v_and_b32_e32 v103, 0xffff0000, v197
	v_lshlrev_b32_e32 v104, 16, v198
	v_and_b32_e32 v105, 0xffff0000, v198
	v_lshlrev_b32_e32 v106, 16, v199
	v_and_b32_e32 v107, 0xffff0000, v199
	v_pk_mul_f32 v[16:17], v[16:17], v[100:101]
	v_pk_mul_f32 v[18:19], v[18:19], v[102:103]
	v_pk_mul_f32 v[20:21], v[20:21], v[104:105]
	v_pk_mul_f32 v[22:23], v[22:23], v[106:107]
	v_cvt_pk_bf16_f32 v16, v16, v17
	v_cvt_pk_bf16_f32 v17, v18, v19
	v_cvt_pk_bf16_f32 v18, v20, v21
	v_cvt_pk_bf16_f32 v19, v22, v23
	global_store_dwordx4 v[68:69], v[16:19], off
	s_waitcnt vmcnt(6)
	v_lshlrev_b32_e32 v108, 16, v200
	v_and_b32_e32 v109, 0xffff0000, v200
	v_lshlrev_b32_e32 v110, 16, v201
	v_and_b32_e32 v111, 0xffff0000, v201
	v_lshlrev_b32_e32 v112, 16, v202
	v_and_b32_e32 v113, 0xffff0000, v202
	v_lshlrev_b32_e32 v114, 16, v203
	v_and_b32_e32 v115, 0xffff0000, v203
	v_pk_mul_f32 v[24:25], v[24:25], v[108:109]
	v_pk_mul_f32 v[26:27], v[26:27], v[110:111]
	v_pk_mul_f32 v[28:29], v[28:29], v[112:113]
	v_pk_mul_f32 v[30:31], v[30:31], v[114:115]
	v_cvt_pk_bf16_f32 v24, v24, v25
	v_cvt_pk_bf16_f32 v25, v26, v27
	v_cvt_pk_bf16_f32 v26, v28, v29
	v_cvt_pk_bf16_f32 v27, v30, v31
	global_store_dwordx4 v[68:69], v[24:27], off offset:32
	s_waitcnt vmcnt(5)
	v_lshlrev_b32_e32 v100, 16, v204
	v_and_b32_e32 v101, 0xffff0000, v204
	v_lshlrev_b32_e32 v102, 16, v205
	v_and_b32_e32 v103, 0xffff0000, v205
	v_lshlrev_b32_e32 v104, 16, v206
	v_and_b32_e32 v105, 0xffff0000, v206
	v_lshlrev_b32_e32 v106, 16, v207
	v_and_b32_e32 v107, 0xffff0000, v207
	v_pk_mul_f32 v[0:1], v[0:1], v[100:101]
	v_pk_mul_f32 v[2:3], v[2:3], v[102:103]
	v_pk_mul_f32 v[4:5], v[4:5], v[104:105]
	v_pk_mul_f32 v[6:7], v[6:7], v[106:107]
	v_cvt_pk_bf16_f32 v0, v0, v1
	v_cvt_pk_bf16_f32 v1, v2, v3
	v_cvt_pk_bf16_f32 v2, v4, v5
	v_cvt_pk_bf16_f32 v3, v6, v7
	global_store_dwordx4 v[68:69], v[0:3], off offset:64
	s_waitcnt vmcnt(4)
	v_lshlrev_b32_e32 v108, 16, v208
	v_and_b32_e32 v109, 0xffff0000, v208
	v_lshlrev_b32_e32 v110, 16, v209
	v_and_b32_e32 v111, 0xffff0000, v209
	v_lshlrev_b32_e32 v112, 16, v210
	v_and_b32_e32 v113, 0xffff0000, v210
	v_lshlrev_b32_e32 v114, 16, v211
	v_and_b32_e32 v115, 0xffff0000, v211
	v_pk_mul_f32 v[8:9], v[8:9], v[108:109]
	v_pk_mul_f32 v[10:11], v[10:11], v[110:111]
	v_pk_mul_f32 v[12:13], v[12:13], v[112:113]
	v_pk_mul_f32 v[14:15], v[14:15], v[114:115]
	v_cvt_pk_bf16_f32 v8, v8, v9
	v_cvt_pk_bf16_f32 v9, v10, v11
	v_cvt_pk_bf16_f32 v10, v12, v13
	v_cvt_pk_bf16_f32 v11, v14, v15
	global_store_dwordx4 v[68:69], v[8:11], off offset:96
	s_cmp_eq_u32 s0, 8
	s_cbranch_scc0 .LBB0_396
	s_add_i32 s3, s3, s90
	s_cmpk_gt_i32 s3, 0xff
	s_cbranch_scc0 .LBB0_387
	s_cmp_eq_u32 s99, 2
	s_cbranch_scc1 .LBB0_425

; DI unsigned xb_add(unsigned* p, unsigned v) { return __hip_atomic_fetch_add(p, v, __ATOMIC_RELAXED, __HIP_MEMORY_SCOPE_AGENT); }
; DI void xcd_barrier(const XcdBarrier& b) {
;   asm volatile("s_waitcnt vmcnt(0)" ::: "memory");
;   __syncthreads();
;   if (threadIdx.x == 0) {
;     unsigned* bar = b.bar;
;     __builtin_amdgcn_s_waitcnt(0);
;     const unsigned nloc = b.nloc, nx = b.nx;
;     const unsigned old = xb_add(&bar[XB_XSUB(b.x)], 1u);
;     const unsigned gen = old / nloc;
;     if (old + 1u == (gen + 1u) * nloc) {
; template <int PH> DI void run_phase(const Params& p, lds_t* shm) {
;     ...
;   else if (PH == 3) { sg_phase(p, shm); diff_attn_phase(p, shm); }
.Lp3_do_sg:
	s_mov_b32 s99, 2
	v_readlane_b32 s40, v194, 0
	v_readlane_b32 s41, v194, 1
	v_readlane_b32 s42, v194, 2
	v_readlane_b32 s43, v194, 3
	v_readlane_b32 s46, v194, 4
	v_readlane_b32 s47, v194, 5
	s_nop 3
	v_mbcnt_lo_u32_b32 v154, -1, 0
	v_mov_b32_e32 v0, v212
	s_waitcnt vmcnt(0) lgkmcnt(0)
	s_branch .Lp3_sg_entry
.LBB0_425:
	s_cmp_eq_u32 s99, 1
	s_cbranch_scc1 .Lp3_do_sg
	s_waitcnt vmcnt(0)
	s_barrier
	s_mov_b64 s[4:5], exec
	v_readlane_b32 s0, v254, 4
	v_readlane_b32 s1, v254, 5
	s_and_b64 s[0:1], s[4:5], s[0:1]
	s_mov_b64 exec, s[0:1]
	s_cbranch_execz .LBB0_462
	s_mov_b64 s[0:1], exec
	v_readlane_b32 s2, v254, 3
	s_lshl_b32 s2, s2, 8
	v_readlane_b32 s6, v254, 1
	v_mbcnt_lo_u32_b32 v0, s0, 0
	v_readlane_b32 s7, v254, 2
	s_add_u32 s6, s6, s2
	v_mbcnt_hi_u32_b32 v0, s1, v0
	s_addc_u32 s7, s7, 0
	v_cmp_eq_u32_e32 vcc, 0, v0
	s_waitcnt vmcnt(0) expcnt(0) lgkmcnt(0)
	s_and_saveexec_b64 s[2:3], vcc
	s_cbranch_execz .LBB0_428
	s_bcnt1_i32_b64 s0, s[0:1]
	v_mov_b32_e32 v1, 0x1000
	v_mov_b32_e32 v2, s0
	global_atomic_add v1, v1, v2, s[6:7] offset:1024 sc0
